# P6 epilogue instruction selection: 41 pairs of in-place f32 squares folded into v_pk_mul_f32 (bit-identical), on top of v15b
# speedup vs baseline: 1.0003x; 1.0003x over previous
; __device__ __forceinline__ unsigned cvt_pk_bf16(float lo, float hi) { unsigned r; asm volatile("v_cvt_pk_bf16_f32 %0, %1, %2" : "=v"(r) : "v"(lo), "v"(hi)); return r; }
;     __device__ __forceinline__ void operator()(const f32x4 (&acc)[2][2][4][2], const Unit& u, int wr, int wc, int fr, int fq) const {
;     ...
;             for (int m = 0; m < 4; ++m) { bf16_t* rowp = O + (size_t)(row0 + ai * HALF + m * 16) * ldc + col0;
;                 const float r2 = 1.0f / (rowsq[row0 + ai * HALF + m * 16] * (1.0f / 2048.0f) + 1e-6f);
; #pragma unroll
;                 for (int bj = 0; bj < 2; ++bj) { f32x4 v0 = acc[ai][bj][m][0], v1 = acc[ai][bj][m][1];
; #pragma unroll
;                     for (int j = 0; j < 4; ++j) { const float a = fmaxf(v0[j], 0.f), b = fmaxf(v1[j], 0.f); v0[j] = a * a * r2; v1[j] = b * b * r2; }
;                     u32x4 w; w.x = cvt_pk_bf16(v0[0], v0[1]); w.y = cvt_pk_bf16(v0[2], v0[3]); w.z = cvt_pk_bf16(v1[0], v1[1]); w.w = cvt_pk_bf16(v1[2], v1[3]);
;                     __builtin_nontemporal_store(w, (u32x4*)(rowp + bj * HALF)); } }
.LBB0_2107:
	v_lshl_add_u32 v144, s30, 8, v1
	v_ashrrev_i32_e32 v145, 31, v144
	v_lshl_add_u64 v[142:143], v[144:145], 2, s[10:11]
	global_load_dword v149, v[142:143], off
	v_lshl_or_b32 v150, s27, 8, v147
	v_ashrrev_i32_e32 v151, 31, v150
	v_max_f32_e32 v153, 0, v116
	v_max_f32_e32 v155, 0, v118
	v_max_f32_e32 v152, 0, v124
	v_max_f32_e32 v154, 0, v117
	v_max_f32_e32 v156, 0, v119
	v_lshlrev_b64 v[118:119], 1, v[150:151]
	v_mul_f32_e32 v151, v153, v153
	v_mul_f32_e32 v153, v155, v155
	v_lshlrev_b64 v[116:117], 14, v[144:145]
	v_mul_f32_e32 v145, v152, v152
	v_mul_f32_e32 v152, v154, v154
	v_mul_f32_e32 v154, v156, v156
	v_max_f32_e32 v128, 0, v128
	v_max_f32_e32 v129, 0, v129
	v_max_f32_e32 v130, 0, v130
	v_max_f32_e32 v131, 0, v131
	v_max_f32_e32 v120, 0, v120
	v_max_f32_e32 v121, 0, v121
	v_max_f32_e32 v125, 0, v125
	v_max_f32_e32 v126, 0, v126
	v_max_f32_e32 v127, 0, v127
	v_max_f32_e32 v122, 0, v122
	v_max_f32_e32 v123, 0, v123
	v_pk_mul_f32 v[128:129], v[128:129], v[128:129]
	v_pk_mul_f32 v[130:131], v[130:131], v[130:131]
	v_pk_mul_f32 v[120:121], v[120:121], v[120:121]
	v_lshl_add_u64 v[116:117], s[8:9], 0, v[116:117]
	v_or_b32_e32 v124, 16, v144
	v_mul_f32_e32 v150, v125, v125
	v_pk_mul_f32 v[126:127], v[126:127], v[126:127]
	v_pk_mul_f32 v[122:123], v[122:123], v[122:123]
	v_lshl_add_u64 v[116:117], v[116:117], 0, v[118:119]
	v_ashrrev_i32_e32 v125, 31, v124
	v_max_f32_e32 v100, 0, v100
	v_max_f32_e32 v101, 0, v101
	v_max_f32_e32 v108, 0, v108
	v_max_f32_e32 v109, 0, v109
	v_max_f32_e32 v112, 0, v112
	v_max_f32_e32 v113, 0, v113
	v_max_f32_e32 v114, 0, v114
	s_waitcnt vmcnt(0)
	v_fmamk_f32 v149, v149, 0x3a000000, v232
	v_div_scale_f32 v155, s[26:27], v149, v149, 1.0
	v_rcp_f32_e32 v156, v155
	v_div_scale_f32 v157, vcc, 1.0, v149, 1.0
	v_max_f32_e32 v110, 0, v110
	v_fma_f32 v158, -v155, v156, 1.0
	v_fmac_f32_e32 v156, v158, v156
	v_mul_f32_e32 v158, v157, v156
	v_fma_f32 v159, -v155, v158, v157
	v_fmac_f32_e32 v158, v159, v156
	v_fma_f32 v155, -v155, v158, v157
	v_div_fmas_f32 v155, v155, v156, v158
	v_div_fixup_f32 v149, v155, v149, 1.0
	v_mul_f32_e32 v128, v128, v149
	v_mul_f32_e32 v129, v129, v149
	v_mul_f32_e32 v130, v130, v149
	v_mul_f32_e32 v131, v131, v149
	v_mul_f32_e32 v155, v120, v149
	v_mul_f32_e32 v156, v121, v149
	v_cvt_pk_bf16_f32 v120, v128, v129
	v_cvt_pk_bf16_f32 v121, v130, v131
	v_mul_f32_e32 v145, v145, v149
	v_mul_f32_e32 v150, v150, v149
	v_mul_f32_e32 v126, v126, v149
	v_mul_f32_e32 v127, v127, v149
	v_mul_f32_e32 v157, v122, v149
	v_mul_f32_e32 v158, v123, v149
	v_cvt_pk_bf16_f32 v122, v145, v150
	v_cvt_pk_bf16_f32 v123, v126, v127
	global_store_dwordx4 v[116:117], v[120:123], off nt
	v_mul_f32_e32 v151, v151, v149
	v_mul_f32_e32 v152, v152, v149
	v_cvt_pk_bf16_f32 v120, v155, v156
	v_cvt_pk_bf16_f32 v121, v157, v158
	v_mul_f32_e32 v153, v153, v149
	v_mul_f32_e32 v149, v154, v149
	v_cvt_pk_bf16_f32 v122, v151, v152
	v_cvt_pk_bf16_f32 v123, v153, v149
	global_store_dwordx4 v[116:117], v[120:123], off offset:256 nt
	v_mul_f32_e32 v126, v100, v100
	v_mul_f32_e32 v128, v101, v101
	v_lshl_add_u64 v[120:121], v[124:125], 2, s[10:11]
	global_load_dword v120, v[120:121], off
	v_lshlrev_b64 v[100:101], 14, v[124:125]
	v_lshl_add_u64 v[100:101], s[8:9], 0, v[100:101]
	v_mul_f32_e32 v122, v108, v108
	v_mul_f32_e32 v123, v109, v109
	v_lshl_add_u64 v[108:109], v[100:101], 0, v[118:119]
	v_max_f32_e32 v115, 0, v115
	v_max_f32_e32 v111, 0, v111
	v_max_f32_e32 v121, 0, v104
	v_max_f32_e32 v105, 0, v105
	v_max_f32_e32 v106, 0, v106
	v_max_f32_e32 v102, 0, v102
	v_max_f32_e32 v107, 0, v107
	v_max_f32_e32 v103, 0, v103
	v_or_b32_e32 v104, 32, v144
	v_pk_mul_f32 v[112:113], v[112:113], v[112:113]
	v_pk_mul_f32 v[114:115], v[114:115], v[114:115]
	v_pk_mul_f32 v[110:111], v[110:111], v[110:111]
	v_mul_f32_e32 v121, v121, v121
	v_mul_f32_e32 v127, v105, v105
	v_mul_f32_e32 v129, v106, v106
	v_mul_f32_e32 v130, v107, v107
	v_pk_mul_f32 v[102:103], v[102:103], v[102:103]
	v_ashrrev_i32_e32 v105, 31, v104
	v_lshl_add_u64 v[106:107], v[104:105], 2, s[10:11]
	v_max_f32_e32 v84, 0, v84
	v_max_f32_e32 v85, 0, v85
	v_max_f32_e32 v92, 0, v92
	v_max_f32_e32 v93, 0, v93
	v_max_f32_e32 v96, 0, v96
	v_max_f32_e32 v97, 0, v97
	v_max_f32_e32 v98, 0, v98
	v_max_f32_e32 v94, 0, v94
	v_max_f32_e32 v99, 0, v99
	v_max_f32_e32 v95, 0, v95
	v_max_f32_e32 v89, 0, v89
	v_max_f32_e32 v90, 0, v90
	v_max_f32_e32 v86, 0, v86
	v_max_f32_e32 v91, 0, v91
	v_max_f32_e32 v87, 0, v87
	v_pk_mul_f32 v[96:97], v[96:97], v[96:97]
	v_pk_mul_f32 v[98:99], v[98:99], v[98:99]
	v_pk_mul_f32 v[94:95], v[94:95], v[94:95]
	v_pk_mul_f32 v[86:87], v[86:87], v[86:87]
	v_max_f32_e32 v68, 0, v68
	v_max_f32_e32 v69, 0, v69
	v_max_f32_e32 v72, 0, v72
	v_max_f32_e32 v73, 0, v73
	s_waitcnt vmcnt(0)
; __device__ __forceinline__ unsigned cvt_pk_bf16(float lo, float hi) { unsigned r; asm volatile("v_cvt_pk_bf16_f32 %0, %1, %2" : "=v"(r) : "v"(lo), "v"(hi)); return r; }
;     __device__ __forceinline__ void operator()(const f32x4 (&acc)[2][2][4][2], const Unit& u, int wr, int wc, int fr, int fq) const {
;     ...
;             for (int m = 0; m < 4; ++m) { bf16_t* rowp = O + (size_t)(row0 + ai * HALF + m * 16) * ldc + col0;
;                 const float r2 = 1.0f / (rowsq[row0 + ai * HALF + m * 16] * (1.0f / 2048.0f) + 1e-6f);
; #pragma unroll
;                 for (int bj = 0; bj < 2; ++bj) { f32x4 v0 = acc[ai][bj][m][0], v1 = acc[ai][bj][m][1];
; #pragma unroll
;                     for (int j = 0; j < 4; ++j) { const float a = fmaxf(v0[j], 0.f), b = fmaxf(v1[j], 0.f); v0[j] = a * a * r2; v1[j] = b * b * r2; }
;                     u32x4 w; w.x = cvt_pk_bf16(v0[0], v0[1]); w.y = cvt_pk_bf16(v0[2], v0[3]); w.z = cvt_pk_bf16(v1[0], v1[1]); w.w = cvt_pk_bf16(v1[2], v1[3]);
;                     __builtin_nontemporal_store(w, (u32x4*)(rowp + bj * HALF)); } }
	v_fmamk_f32 v120, v120, 0x3a000000, v232
	v_div_scale_f32 v124, s[26:27], v120, v120, 1.0
	v_rcp_f32_e32 v125, v124
	v_div_scale_f32 v100, vcc, 1.0, v120, 1.0
	v_fma_f32 v101, -v124, v125, 1.0
	v_fmac_f32_e32 v125, v101, v125
	v_mul_f32_e32 v101, v100, v125
	v_fma_f32 v131, -v124, v101, v100
	v_fmac_f32_e32 v101, v131, v125
	v_fma_f32 v100, -v124, v101, v100
	v_div_fmas_f32 v100, v100, v125, v101
	v_div_fixup_f32 v100, v100, v120, 1.0
	v_mul_f32_e32 v101, v112, v100
	v_mul_f32_e32 v112, v122, v100
	v_mul_f32_e32 v113, v113, v100
	v_mul_f32_e32 v120, v123, v100
	v_mul_f32_e32 v114, v114, v100
	v_mul_f32_e32 v110, v110, v100
	v_mul_f32_e32 v115, v115, v100
	v_mul_f32_e32 v111, v111, v100
	v_mul_f32_e32 v121, v121, v100
	v_mul_f32_e32 v122, v126, v100
	v_mul_f32_e32 v123, v127, v100
	v_mul_f32_e32 v124, v128, v100
	v_mul_f32_e32 v125, v129, v100
	v_mul_f32_e32 v126, v102, v100
	v_mul_f32_e32 v127, v130, v100
	v_mul_f32_e32 v128, v103, v100
	v_cvt_pk_bf16_f32 v100, v101, v113
	v_cvt_pk_bf16_f32 v101, v114, v115
	v_cvt_pk_bf16_f32 v102, v112, v120
	v_cvt_pk_bf16_f32 v103, v110, v111
	global_store_dwordx4 v[108:109], v[100:103], off nt
	v_mul_f32_e32 v110, v91, v91
	s_nop 0
	v_cvt_pk_bf16_f32 v100, v121, v123
	v_cvt_pk_bf16_f32 v101, v125, v127
	v_cvt_pk_bf16_f32 v102, v122, v124
	v_cvt_pk_bf16_f32 v103, v126, v128
	global_store_dwordx4 v[108:109], v[100:103], off offset:256 nt
	global_load_dword v100, v[106:107], off
	v_mul_f32_e32 v106, v84, v84
	v_mul_f32_e32 v108, v85, v85
	v_lshlrev_b64 v[84:85], 14, v[104:105]
	v_lshl_add_u64 v[84:85], s[8:9], 0, v[84:85]
	v_mul_f32_e32 v102, v92, v92
	v_mul_f32_e32 v103, v93, v93
	v_lshl_add_u64 v[92:93], v[84:85], 0, v[118:119]
	v_max_f32_e32 v101, 0, v88
	v_or_b32_e32 v88, 48, v144
	v_mul_f32_e32 v101, v101, v101
	v_mul_f32_e32 v107, v89, v89
	v_mul_f32_e32 v109, v90, v90
	v_ashrrev_i32_e32 v89, 31, v88
	v_lshl_add_u64 v[90:91], v[88:89], 2, s[10:11]
	v_max_f32_e32 v80, 0, v80
	v_max_f32_e32 v76, 0, v76
	v_max_f32_e32 v81, 0, v81
	v_max_f32_e32 v77, 0, v77
	v_max_f32_e32 v82, 0, v82
	v_max_f32_e32 v78, 0, v78
	v_max_f32_e32 v83, 0, v83
	v_max_f32_e32 v79, 0, v79
	v_max_f32_e32 v74, 0, v74
	v_max_f32_e32 v70, 0, v70
	v_max_f32_e32 v75, 0, v75
	v_max_f32_e32 v71, 0, v71
	v_pk_mul_f32 v[80:81], v[80:81], v[80:81]
	v_pk_mul_f32 v[76:77], v[76:77], v[76:77]
	v_pk_mul_f32 v[82:83], v[82:83], v[82:83]
	v_pk_mul_f32 v[78:79], v[78:79], v[78:79]
	v_pk_mul_f32 v[74:75], v[74:75], v[74:75]
	v_pk_mul_f32 v[70:71], v[70:71], v[70:71]
	v_max_f32_e32 v56, 0, v56
	v_max_f32_e32 v57, 0, v57
	v_max_f32_e32 v58, 0, v58
	s_mov_b32 s15, 0x200000
	v_max_f32_e32 v59, 0, v59
	v_max_f32_e32 v64, 0, v64
	v_max_f32_e32 v60, 0, v60
	v_max_f32_e32 v65, 0, v65
	v_max_f32_e32 v61, 0, v61
	v_max_f32_e32 v66, 0, v66
	v_max_f32_e32 v62, 0, v62
	v_max_f32_e32 v67, 0, v67
	v_max_f32_e32 v63, 0, v63
	v_max_f32_e32 v52, 0, v52
	v_max_f32_e32 v53, 0, v53
	v_max_f32_e32 v54, 0, v54
	v_max_f32_e32 v55, 0, v55
	v_mul_f32_e32 v60, v60, v60
	s_waitcnt vmcnt(0)
	v_fmamk_f32 v100, v100, 0x3a000000, v232
	v_div_scale_f32 v104, s[26:27], v100, v100, 1.0
	v_rcp_f32_e32 v105, v104
	v_div_scale_f32 v84, vcc, 1.0, v100, 1.0
	v_pk_mul_f32 v[64:65], v[64:65], v[64:65]
	v_fma_f32 v85, -v104, v105, 1.0
	v_fmac_f32_e32 v105, v85, v105
	v_mul_f32_e32 v85, v84, v105
	v_fma_f32 v111, -v104, v85, v84
	v_fmac_f32_e32 v85, v111, v105
	v_fma_f32 v84, -v104, v85, v84
	v_div_fmas_f32 v84, v84, v105, v85
	v_div_fixup_f32 v84, v84, v100, 1.0
	v_mul_f32_e32 v85, v96, v84
	v_mul_f32_e32 v96, v102, v84
	v_mul_f32_e32 v97, v97, v84
	v_mul_f32_e32 v100, v103, v84
	v_mul_f32_e32 v98, v98, v84
	v_mul_f32_e32 v94, v94, v84
	v_mul_f32_e32 v99, v99, v84
	v_mul_f32_e32 v95, v95, v84
	v_mul_f32_e32 v101, v101, v84
	v_mul_f32_e32 v102, v106, v84
	v_mul_f32_e32 v103, v107, v84
	v_mul_f32_e32 v104, v108, v84
	v_mul_f32_e32 v105, v109, v84
	v_mul_f32_e32 v106, v86, v84
	v_mul_f32_e32 v107, v110, v84
	v_mul_f32_e32 v108, v87, v84
	v_cvt_pk_bf16_f32 v84, v85, v97
	v_cvt_pk_bf16_f32 v85, v98, v99
	v_cvt_pk_bf16_f32 v86, v96, v100
	v_cvt_pk_bf16_f32 v87, v94, v95
	global_store_dwordx4 v[92:93], v[84:87], off nt
	v_mul_f32_e32 v61, v61, v61
	v_mul_f32_e32 v66, v66, v66
	v_cvt_pk_bf16_f32 v84, v101, v103
	v_cvt_pk_bf16_f32 v85, v105, v107
	v_cvt_pk_bf16_f32 v86, v102, v104
	v_cvt_pk_bf16_f32 v87, v106, v108
	global_store_dwordx4 v[92:93], v[84:87], off offset:256 nt
	global_load_dword v84, v[90:91], off
	v_mul_f32_e32 v90, v69, v69
	v_mul_f32_e32 v86, v68, v68
	v_lshlrev_b64 v[68:69], 14, v[88:89]
	v_lshl_add_u64 v[68:69], s[8:9], 0, v[68:69]
	v_mul_f32_e32 v85, v72, v72
	v_mul_f32_e32 v87, v73, v73
	v_lshl_add_u64 v[72:73], v[68:69], 0, v[118:119]
	v_mul_f32_e32 v67, v67, v67
	v_pk_mul_f32 v[62:63], v[62:63], v[62:63]
	v_pk_mul_f32 v[52:53], v[52:53], v[52:53]
	v_pk_mul_f32 v[54:55], v[54:55], v[54:55]
	v_max_f32_e32 v40, 0, v40
	v_max_f32_e32 v41, 0, v41
	v_max_f32_e32 v42, 0, v42
	v_max_f32_e32 v43, 0, v43
	v_max_f32_e32 v48, 0, v48
	v_max_f32_e32 v44, 0, v44
	v_max_f32_e32 v49, 0, v49
	v_max_f32_e32 v45, 0, v45
	v_max_f32_e32 v50, 0, v50
	v_max_f32_e32 v46, 0, v46
	v_max_f32_e32 v51, 0, v51
	v_max_f32_e32 v47, 0, v47
	v_max_f32_e32 v36, 0, v36
	v_max_f32_e32 v37, 0, v37
	v_max_f32_e32 v38, 0, v38
	v_max_f32_e32 v39, 0, v39
	v_pk_mul_f32 v[48:49], v[48:49], v[48:49]
	v_pk_mul_f32 v[44:45], v[44:45], v[44:45]
	v_pk_mul_f32 v[50:51], v[50:51], v[50:51]
	v_pk_mul_f32 v[46:47], v[46:47], v[46:47]
	v_pk_mul_f32 v[36:37], v[36:37], v[36:37]
	v_pk_mul_f32 v[38:39], v[38:39], v[38:39]
	v_max_f32_e32 v24, 0, v24
	v_max_f32_e32 v25, 0, v25
	v_max_f32_e32 v26, 0, v26
	v_max_f32_e32 v27, 0, v27
	v_max_f32_e32 v32, 0, v32
	s_waitcnt vmcnt(0)
; __device__ __forceinline__ unsigned cvt_pk_bf16(float lo, float hi) { unsigned r; asm volatile("v_cvt_pk_bf16_f32 %0, %1, %2" : "=v"(r) : "v"(lo), "v"(hi)); return r; }
;     __device__ __forceinline__ void operator()(const f32x4 (&acc)[2][2][4][2], const Unit& u, int wr, int wc, int fr, int fq) const {
;     ...
;             for (int m = 0; m < 4; ++m) { bf16_t* rowp = O + (size_t)(row0 + ai * HALF + m * 16) * ldc + col0;
;                 const float r2 = 1.0f / (rowsq[row0 + ai * HALF + m * 16] * (1.0f / 2048.0f) + 1e-6f);
; #pragma unroll
;                 for (int bj = 0; bj < 2; ++bj) { f32x4 v0 = acc[ai][bj][m][0], v1 = acc[ai][bj][m][1];
; #pragma unroll
;                     for (int j = 0; j < 4; ++j) { const float a = fmaxf(v0[j], 0.f), b = fmaxf(v1[j], 0.f); v0[j] = a * a * r2; v1[j] = b * b * r2; }
;                     u32x4 w; w.x = cvt_pk_bf16(v0[0], v0[1]); w.y = cvt_pk_bf16(v0[2], v0[3]); w.z = cvt_pk_bf16(v1[0], v1[1]); w.w = cvt_pk_bf16(v1[2], v1[3]);
;                     __builtin_nontemporal_store(w, (u32x4*)(rowp + bj * HALF)); } }
	v_fmamk_f32 v84, v84, 0x3a000000, v232
	v_div_scale_f32 v88, s[26:27], v84, v84, 1.0
	v_rcp_f32_e32 v89, v88
	v_div_scale_f32 v68, vcc, 1.0, v84, 1.0
	s_mov_b64 s[26:27], 0x200000
	v_fma_f32 v69, -v88, v89, 1.0
	v_fmac_f32_e32 v89, v69, v89
	v_mul_f32_e32 v69, v68, v89
	v_fma_f32 v91, -v88, v69, v68
	v_fmac_f32_e32 v69, v91, v89
	v_fma_f32 v68, -v88, v69, v68
	v_div_fmas_f32 v68, v68, v89, v69
	v_div_fixup_f32 v68, v68, v84, 1.0
	v_mul_f32_e32 v69, v80, v68
	v_mul_f32_e32 v76, v76, v68
	v_mul_f32_e32 v80, v81, v68
	v_mul_f32_e32 v77, v77, v68
	v_mul_f32_e32 v81, v82, v68
	v_mul_f32_e32 v78, v78, v68
	v_mul_f32_e32 v82, v83, v68
	v_mul_f32_e32 v79, v79, v68
	v_mul_f32_e32 v83, v85, v68
	v_mul_f32_e32 v84, v86, v68
	v_mul_f32_e32 v85, v87, v68
	v_mul_f32_e32 v86, v90, v68
	v_mul_f32_e32 v74, v74, v68
	v_mul_f32_e32 v87, v70, v68
	v_mul_f32_e32 v75, v75, v68
	v_mul_f32_e32 v88, v71, v68
	v_cvt_pk_bf16_f32 v68, v69, v80
	v_cvt_pk_bf16_f32 v69, v81, v82
	v_cvt_pk_bf16_f32 v70, v76, v77
	v_cvt_pk_bf16_f32 v71, v78, v79
	global_store_dwordx4 v[72:73], v[68:71], off nt
	v_max_f32_e32 v28, 0, v28
	v_max_f32_e32 v33, 0, v33
	v_cvt_pk_bf16_f32 v68, v83, v85
	v_cvt_pk_bf16_f32 v69, v74, v75
	v_cvt_pk_bf16_f32 v70, v84, v86
	v_cvt_pk_bf16_f32 v71, v87, v88
	global_store_dwordx4 v[72:73], v[68:71], off offset:256 nt
	global_load_dword v68, v[142:143], off offset:512
	v_mul_f32_e32 v72, v59, v59
	v_mul_f32_e32 v69, v56, v56
	v_mul_f32_e32 v70, v57, v57
	v_lshl_add_u64 v[56:57], v[116:117], 0, s[26:27]
	v_mul_f32_e32 v71, v58, v58
	v_add_co_u32_e32 v58, vcc, s15, v116
	s_mov_b32 s15, 0x240000
	s_nop 0
	v_addc_co_u32_e32 v59, vcc, 0, v117, vcc
	v_max_f32_e32 v29, 0, v29
	v_max_f32_e32 v34, 0, v34
	v_max_f32_e32 v30, 0, v30
	v_max_f32_e32 v35, 0, v35
	v_max_f32_e32 v31, 0, v31
	v_max_f32_e32 v20, 0, v20
	v_max_f32_e32 v21, 0, v21
	v_max_f32_e32 v22, 0, v22
	v_max_f32_e32 v23, 0, v23
	v_pk_mul_f32 v[32:33], v[32:33], v[32:33]
	v_pk_mul_f32 v[28:29], v[28:29], v[28:29]
	v_pk_mul_f32 v[34:35], v[34:35], v[34:35]
	v_pk_mul_f32 v[30:31], v[30:31], v[30:31]
	v_pk_mul_f32 v[20:21], v[20:21], v[20:21]
	v_pk_mul_f32 v[22:23], v[22:23], v[22:23]
	v_max_f32_e32 v8, 0, v8
	v_max_f32_e32 v9, 0, v9
	v_max_f32_e32 v10, 0, v10
	v_max_f32_e32 v11, 0, v11
	v_max_f32_e32 v16, 0, v16
	v_max_f32_e32 v12, 0, v12
	v_max_f32_e32 v17, 0, v17
	v_max_f32_e32 v13, 0, v13
	v_max_f32_e32 v18, 0, v18
	v_max_f32_e32 v14, 0, v14
	v_max_f32_e32 v19, 0, v19
	v_max_f32_e32 v15, 0, v15
	v_max_f32_e32 v4, 0, v4
	v_max_f32_e32 v5, 0, v5
	v_max_f32_e32 v6, 0, v6
	v_max_f32_e32 v7, 0, v7
	v_pk_mul_f32 v[16:17], v[16:17], v[16:17]
	v_pk_mul_f32 v[12:13], v[12:13], v[12:13]
	v_pk_mul_f32 v[18:19], v[18:19], v[18:19]
	v_pk_mul_f32 v[14:15], v[14:15], v[14:15]
	v_pk_mul_f32 v[4:5], v[4:5], v[4:5]
	v_pk_mul_f32 v[6:7], v[6:7], v[6:7]
	s_waitcnt vmcnt(0)
	v_fmamk_f32 v68, v68, 0x3a000000, v232
	v_div_scale_f32 v73, s[26:27], v68, v68, 1.0
	v_rcp_f32_e32 v74, v73
	v_div_scale_f32 v75, vcc, 1.0, v68, 1.0
	s_mov_b64 s[26:27], 0x240000
	v_fma_f32 v76, -v73, v74, 1.0
	v_fmac_f32_e32 v74, v76, v74
	v_mul_f32_e32 v76, v75, v74
	v_fma_f32 v77, -v73, v76, v75
	v_fmac_f32_e32 v76, v77, v74
	v_fma_f32 v73, -v73, v76, v75
	v_div_fmas_f32 v73, v73, v74, v76
	v_div_fixup_f32 v68, v73, v68, 1.0
	v_mul_f32_e32 v64, v64, v68
	v_mul_f32_e32 v60, v60, v68
	v_mul_f32_e32 v65, v65, v68
	v_mul_f32_e32 v61, v61, v68
	v_mul_f32_e32 v66, v66, v68
	v_mul_f32_e32 v62, v62, v68
	v_mul_f32_e32 v67, v67, v68
	v_mul_f32_e32 v63, v63, v68
	v_mul_f32_e32 v69, v69, v68
	v_mul_f32_e32 v73, v52, v68
	v_mul_f32_e32 v70, v70, v68
	v_mul_f32_e32 v74, v53, v68
	v_mul_f32_e32 v71, v71, v68
	v_mul_f32_e32 v75, v54, v68
	v_mul_f32_e32 v72, v72, v68
	v_mul_f32_e32 v68, v55, v68
	v_cvt_pk_bf16_f32 v52, v64, v65
	v_cvt_pk_bf16_f32 v53, v66, v67
	v_cvt_pk_bf16_f32 v54, v60, v61
	v_cvt_pk_bf16_f32 v55, v62, v63
	global_store_dwordx4 v[58:59], v[52:55], off nt
	s_nop 1
	v_cvt_pk_bf16_f32 v52, v69, v70
	v_cvt_pk_bf16_f32 v53, v71, v72
	v_cvt_pk_bf16_f32 v54, v73, v74
	v_cvt_pk_bf16_f32 v55, v75, v68
	global_store_dwordx4 v[56:57], v[52:55], off offset:256 nt
	global_load_dword v52, v[142:143], off offset:576
	v_mul_f32_e32 v56, v43, v43
	v_mul_f32_e32 v53, v40, v40
	v_mul_f32_e32 v54, v41, v41
	v_lshl_add_u64 v[40:41], v[116:117], 0, s[26:27]
	v_mul_f32_e32 v55, v42, v42
	v_add_co_u32_e32 v42, vcc, s15, v116
	s_mov_b32 s15, 0x280000
	s_nop 0
	v_addc_co_u32_e32 v43, vcc, 0, v117, vcc
	s_waitcnt vmcnt(0)
; __device__ __forceinline__ unsigned cvt_pk_bf16(float lo, float hi) { unsigned r; asm volatile("v_cvt_pk_bf16_f32 %0, %1, %2" : "=v"(r) : "v"(lo), "v"(hi)); return r; }
;     __device__ __forceinline__ void operator()(const f32x4 (&acc)[2][2][4][2], const Unit& u, int wr, int wc, int fr, int fq) const {
;     ...
;             for (int m = 0; m < 4; ++m) { bf16_t* rowp = O + (size_t)(row0 + ai * HALF + m * 16) * ldc + col0;
;                 const float r2 = 1.0f / (rowsq[row0 + ai * HALF + m * 16] * (1.0f / 2048.0f) + 1e-6f);
; #pragma unroll
;                 for (int bj = 0; bj < 2; ++bj) { f32x4 v0 = acc[ai][bj][m][0], v1 = acc[ai][bj][m][1];
; #pragma unroll
;                     for (int j = 0; j < 4; ++j) { const float a = fmaxf(v0[j], 0.f), b = fmaxf(v1[j], 0.f); v0[j] = a * a * r2; v1[j] = b * b * r2; }
;                     u32x4 w; w.x = cvt_pk_bf16(v0[0], v0[1]); w.y = cvt_pk_bf16(v0[2], v0[3]); w.z = cvt_pk_bf16(v1[0], v1[1]); w.w = cvt_pk_bf16(v1[2], v1[3]);
;                     __builtin_nontemporal_store(w, (u32x4*)(rowp + bj * HALF)); } }
	v_fmamk_f32 v52, v52, 0x3a000000, v232
	v_div_scale_f32 v57, s[26:27], v52, v52, 1.0
	v_rcp_f32_e32 v58, v57
	v_div_scale_f32 v59, vcc, 1.0, v52, 1.0
	s_mov_b64 s[26:27], 0x280000
	v_fma_f32 v60, -v57, v58, 1.0
	v_fmac_f32_e32 v58, v60, v58
	v_mul_f32_e32 v60, v59, v58
	v_fma_f32 v61, -v57, v60, v59
	v_fmac_f32_e32 v60, v61, v58
	v_fma_f32 v57, -v57, v60, v59
	v_div_fmas_f32 v57, v57, v58, v60
	v_div_fixup_f32 v52, v57, v52, 1.0
	v_mul_f32_e32 v48, v48, v52
	v_mul_f32_e32 v44, v44, v52
	v_mul_f32_e32 v49, v49, v52
	v_mul_f32_e32 v45, v45, v52
	v_mul_f32_e32 v50, v50, v52
	v_mul_f32_e32 v46, v46, v52
	v_mul_f32_e32 v51, v51, v52
	v_mul_f32_e32 v47, v47, v52
	v_mul_f32_e32 v53, v53, v52
	v_mul_f32_e32 v57, v36, v52
	v_mul_f32_e32 v54, v54, v52
	v_mul_f32_e32 v58, v37, v52
	v_mul_f32_e32 v55, v55, v52
	v_mul_f32_e32 v59, v38, v52
	v_mul_f32_e32 v56, v56, v52
	v_mul_f32_e32 v52, v39, v52
	v_cvt_pk_bf16_f32 v36, v48, v49
	v_cvt_pk_bf16_f32 v37, v50, v51
	v_cvt_pk_bf16_f32 v38, v44, v45
	v_cvt_pk_bf16_f32 v39, v46, v47
	global_store_dwordx4 v[42:43], v[36:39], off nt
	s_nop 1
	v_cvt_pk_bf16_f32 v36, v53, v54
	v_cvt_pk_bf16_f32 v37, v55, v56
	v_cvt_pk_bf16_f32 v38, v57, v58
	v_cvt_pk_bf16_f32 v39, v59, v52
	global_store_dwordx4 v[40:41], v[36:39], off offset:256 nt
	global_load_dword v36, v[142:143], off offset:640
	v_mul_f32_e32 v40, v27, v27
	v_mul_f32_e32 v37, v24, v24
	v_mul_f32_e32 v38, v25, v25
	v_lshl_add_u64 v[24:25], v[116:117], 0, s[26:27]
	v_mul_f32_e32 v39, v26, v26
	v_add_co_u32_e32 v26, vcc, s15, v116
	s_mov_b32 s15, 0x2c0000
	s_nop 0
	v_addc_co_u32_e32 v27, vcc, 0, v117, vcc
	s_waitcnt vmcnt(0)
	v_fmamk_f32 v36, v36, 0x3a000000, v232
	v_div_scale_f32 v41, s[26:27], v36, v36, 1.0
	v_rcp_f32_e32 v42, v41
	v_div_scale_f32 v43, vcc, 1.0, v36, 1.0
	s_mov_b64 s[26:27], 0x2c0000
	v_fma_f32 v44, -v41, v42, 1.0
	v_fmac_f32_e32 v42, v44, v42
	v_mul_f32_e32 v44, v43, v42
	v_fma_f32 v45, -v41, v44, v43
	v_fmac_f32_e32 v44, v45, v42
	v_fma_f32 v41, -v41, v44, v43
	v_div_fmas_f32 v41, v41, v42, v44
	v_div_fixup_f32 v36, v41, v36, 1.0
	v_mul_f32_e32 v32, v32, v36
	v_mul_f32_e32 v28, v28, v36
	v_mul_f32_e32 v33, v33, v36
	v_mul_f32_e32 v29, v29, v36
	v_mul_f32_e32 v34, v34, v36
	v_mul_f32_e32 v30, v30, v36
	v_mul_f32_e32 v35, v35, v36
	v_mul_f32_e32 v31, v31, v36
	v_mul_f32_e32 v37, v37, v36
	v_mul_f32_e32 v41, v20, v36
	v_mul_f32_e32 v38, v38, v36
	v_mul_f32_e32 v42, v21, v36
	v_mul_f32_e32 v39, v39, v36
	v_mul_f32_e32 v43, v22, v36
	v_mul_f32_e32 v40, v40, v36
	v_mul_f32_e32 v36, v23, v36
	v_cvt_pk_bf16_f32 v20, v32, v33
	v_cvt_pk_bf16_f32 v21, v34, v35
	v_cvt_pk_bf16_f32 v22, v28, v29
	v_cvt_pk_bf16_f32 v23, v30, v31
	global_store_dwordx4 v[26:27], v[20:23], off nt
	s_nop 1
	v_cvt_pk_bf16_f32 v20, v37, v38
	v_cvt_pk_bf16_f32 v21, v39, v40
	v_cvt_pk_bf16_f32 v22, v41, v42
	v_cvt_pk_bf16_f32 v23, v43, v36
	global_store_dwordx4 v[24:25], v[20:23], off offset:256 nt
	global_load_dword v20, v[142:143], off offset:704
	v_mul_f32_e32 v24, v11, v11
	v_mul_f32_e32 v21, v8, v8
	v_mul_f32_e32 v22, v9, v9
	v_lshl_add_u64 v[8:9], v[116:117], 0, s[26:27]
	v_mul_f32_e32 v23, v10, v10
	v_add_co_u32_e32 v10, vcc, s15, v116
	s_waitcnt vmcnt(0)
	v_fmamk_f32 v20, v20, 0x3a000000, v232
	v_div_scale_f32 v25, s[26:27], v20, v20, 1.0
	v_rcp_f32_e32 v26, v25
	v_addc_co_u32_e32 v11, vcc, 0, v117, vcc
	v_div_scale_f32 v27, vcc, 1.0, v20, 1.0
	v_fma_f32 v28, -v25, v26, 1.0
	v_fmac_f32_e32 v26, v28, v26
	v_mul_f32_e32 v28, v27, v26
	v_fma_f32 v29, -v25, v28, v27
	v_fmac_f32_e32 v28, v29, v26
	v_fma_f32 v25, -v25, v28, v27
	v_div_fmas_f32 v25, v25, v26, v28
	v_div_fixup_f32 v20, v25, v20, 1.0
	s_andn2_b64 vcc, exec, s[4:5]
	v_mul_f32_e32 v16, v16, v20
	v_mul_f32_e32 v12, v12, v20
	v_mul_f32_e32 v17, v17, v20
	v_mul_f32_e32 v13, v13, v20
	v_mul_f32_e32 v18, v18, v20
	v_mul_f32_e32 v14, v14, v20
	v_mul_f32_e32 v19, v19, v20
	v_mul_f32_e32 v15, v15, v20
	v_mul_f32_e32 v21, v21, v20
	v_mul_f32_e32 v25, v4, v20
	v_mul_f32_e32 v22, v22, v20
	v_mul_f32_e32 v26, v5, v20
	v_mul_f32_e32 v23, v23, v20
	v_mul_f32_e32 v27, v6, v20
	v_mul_f32_e32 v24, v24, v20
	v_mul_f32_e32 v20, v7, v20
	v_cvt_pk_bf16_f32 v4, v16, v17
	v_cvt_pk_bf16_f32 v5, v18, v19
	v_cvt_pk_bf16_f32 v6, v12, v13
	v_cvt_pk_bf16_f32 v7, v14, v15
	s_mov_b64 s[4:5], -1
	global_store_dwordx4 v[10:11], v[4:7], off nt
	s_nop 1
	v_cvt_pk_bf16_f32 v4, v21, v22
	v_cvt_pk_bf16_f32 v5, v23, v24
	v_cvt_pk_bf16_f32 v6, v25, v26
	v_cvt_pk_bf16_f32 v7, v27, v20
	global_store_dwordx4 v[8:9], v[4:7], off offset:256 nt
	s_cbranch_vccnz .LBB0_2096
	s_andn2_b64 vcc, exec, s[6:7]
	s_cbranch_vccnz .LBB0_2095
	s_barrier
	s_branch .LBB0_2095
